# P2 gate loads issued before barrier 1
# baseline (speedup 1.0000x reference)
.LBB0_217:
	s_or_b64 exec, exec, s[6:7]
	s_waitcnt lgkmcnt(2)
	v_readlane_b32 s6, v255, 10
	v_and_b32_e32 v2, 1, v88
	v_lshrrev_b32_e32 v30, 1, v88
	v_or_b32_e32 v21, s6, v54
	v_lshlrev_b32_e32 v2, 5, v2
	v_lshl_or_b32 v2, v30, 4, v2
	v_add_u32_e32 v2, v56, v2
	v_add_u32_e32 v2, 0x1c00, v2
	s_add_u32 s6, s39, s54
	s_addc_u32 s7, s78, s55
	v_lshl_add_u64 v[22:23], s[6:7], 0, v[2:3]
	v_add_co_u32_e32 v22, vcc, s63, v22
	s_nop 1
	v_addc_co_u32_e32 v23, vcc, 0, v23, vcc
	global_load_dwordx4 v[238:241], v[22:23], off
	global_load_dwordx4 v[242:245], v[22:23], off offset:64
	global_load_dwordx4 v[246:249], v[22:23], off offset:2048
	global_load_dwordx4 v[250:253], v[22:23], off offset:2112
	global_load_dwordx4 v[154:157], v[22:23], off offset:-2048
	global_load_dwordx4 v[216:219], v[22:23], off offset:-1984
	s_waitcnt lgkmcnt(0)
	s_barrier
	v_mul_lo_u32 v20, v55, s60
	v_add_lshl_u32 v20, v21, v20, 1
	v_mov_b32_e32 v21, v3
	v_lshl_add_u64 v[20:21], s[6:7], 0, v[20:21]
	s_lshl_b32 s6, s41, 8
	s_add_i32 s6, s6, 0
	s_mov_b32 s101, 0
	v_cmp_lt_u32_e64 s[20:21], 1, v88
	v_cmp_eq_u32_e64 s[22:23], 3, v88
	v_add_u32_e32 v2, s6, v89
	v_add_u32_e32 v2, 0x20800, v2
	v_add_u32_e32 v32, 0x1f800, v89
	ds_read_b32 v36, v2
	ds_read_b32 v37, v2 offset:64
	ds_read_b32 v38, v2 offset:128
	ds_read_b32 v39, v2 offset:192
	v_add_u32_e32 v33, 64, v32
	v_add_u32_e32 v34, 0x80, v32
	v_add_u32_e32 v35, 0xc0, v32
	ds_read2st64_b32 v[160:161], v32 offset1:8
	ds_read2st64_b32 v[162:163], v33 offset1:8
	ds_read2st64_b32 v[164:165], v34 offset1:8
	ds_read2st64_b32 v[166:167], v35 offset1:8
	ds_read2st64_b32 v[168:169], v32 offset0:1 offset1:9
	ds_read2st64_b32 v[170:171], v33 offset0:1 offset1:9
	ds_read2st64_b32 v[172:173], v34 offset0:1 offset1:9
	ds_read2st64_b32 v[174:175], v35 offset0:1 offset1:9
	ds_read2st64_b32 v[176:177], v32 offset0:2 offset1:10
	ds_read2st64_b32 v[178:179], v33 offset0:2 offset1:10
	ds_read2st64_b32 v[180:181], v34 offset0:2 offset1:10
	ds_read2st64_b32 v[182:183], v35 offset0:2 offset1:10
	ds_read2st64_b32 v[184:185], v32 offset0:3 offset1:11
	ds_read2st64_b32 v[186:187], v33 offset0:3 offset1:11
	ds_read2st64_b32 v[188:189], v34 offset0:3 offset1:11
	ds_read2st64_b32 v[190:191], v35 offset0:3 offset1:11
	ds_read2st64_b32 v[192:193], v32 offset0:4 offset1:12
	ds_read2st64_b32 v[194:195], v33 offset0:4 offset1:12
	ds_read2st64_b32 v[196:197], v34 offset0:4 offset1:12
	ds_read2st64_b32 v[198:199], v35 offset0:4 offset1:12
	ds_read2st64_b32 v[200:201], v32 offset0:5 offset1:13
	ds_read2st64_b32 v[202:203], v33 offset0:5 offset1:13
	ds_read2st64_b32 v[204:205], v34 offset0:5 offset1:13
	ds_read2st64_b32 v[206:207], v35 offset0:5 offset1:13
	ds_read2st64_b32 v[208:209], v32 offset0:6 offset1:14
	ds_read2st64_b32 v[210:211], v33 offset0:6 offset1:14
	ds_read2st64_b32 v[212:213], v34 offset0:6 offset1:14
	ds_read2st64_b32 v[214:215], v35 offset0:6 offset1:14
	ds_read2_b32 v[220:221], v106 offset1:68
	ds_read2_b32 v[222:223], v106 offset0:136 offset1:204
	ds_read2_b32 v[224:225], v106 offset0:16 offset1:84
	ds_read2_b32 v[226:227], v106 offset0:152 offset1:220
	ds_read2_b32 v[230:231], v106 offset0:32 offset1:100
	ds_read2_b32 v[232:233], v106 offset0:168 offset1:236
	ds_read2_b32 v[234:235], v106 offset0:48 offset1:116
	ds_read2_b32 v[236:237], v106 offset0:184 offset1:252
	s_xor_b32 s96, s41, 1
	v_readlane_b32 s56, v255, 17
	v_readlane_b32 s57, v255, 18
	s_lshl_b32 s58, s96, 8
	s_add_i32 s58, s58, 0x20800
	v_add_u32_e32 v31, s58, v89
	s_and_b64 s[56:57], s[56:57], s[22:23]
	v_cndmask_b32_e64 v22, v136, 0, s[0:1]
	v_cndmask_b32_e64 v23, v122, 1.0, s[0:1]
	v_fmac_f32_e32 v132, v22, v123
	v_mul_f32_e32 v30, v23, v123
	v_cndmask_b32_e64 v22, v22, v132, s[20:21]
	v_cndmask_b32_e64 v23, v23, v30, s[20:21]
	v_fmac_f32_e32 v131, v22, v120
	v_mul_f32_e32 v30, v23, v120
	v_cndmask_b32_e64 v22, v22, v131, s[22:23]
	v_cndmask_b32_e64 v23, v23, v30, s[22:23]
	v_cndmask_b32_e64 v24, v130, 0, s[0:1]
	v_cndmask_b32_e64 v25, v126, 1.0, s[0:1]
	v_fmac_f32_e32 v129, v24, v128
	v_mul_f32_e32 v30, v25, v128
	v_cndmask_b32_e64 v24, v24, v129, s[20:21]
	v_cndmask_b32_e64 v25, v25, v30, s[20:21]
	v_fmac_f32_e32 v125, v24, v124
	v_mul_f32_e32 v30, v25, v124
	v_cndmask_b32_e64 v24, v24, v125, s[22:23]
	v_cndmask_b32_e64 v25, v25, v30, s[22:23]
	v_cndmask_b32_e64 v26, v139, 0, s[0:1]
	v_cndmask_b32_e64 v27, v135, 1.0, s[0:1]
	v_fmac_f32_e32 v138, v26, v137
	v_mul_f32_e32 v30, v27, v137
	v_cndmask_b32_e64 v26, v26, v138, s[20:21]
	v_cndmask_b32_e64 v27, v27, v30, s[20:21]
	v_fmac_f32_e32 v134, v26, v133
	v_mul_f32_e32 v30, v27, v133
	v_cndmask_b32_e64 v26, v26, v134, s[22:23]
	v_cndmask_b32_e64 v27, v27, v30, s[22:23]
	v_cndmask_b32_e64 v28, v146, 0, s[0:1]
	v_cndmask_b32_e64 v29, v142, 1.0, s[0:1]
	v_fmac_f32_e32 v145, v28, v143
	v_mul_f32_e32 v30, v29, v143
	v_cndmask_b32_e64 v28, v28, v145, s[20:21]
	v_cndmask_b32_e64 v29, v29, v30, s[20:21]
	v_fmac_f32_e32 v141, v28, v140
	v_mul_f32_e32 v30, v29, v140
	v_cndmask_b32_e64 v28, v28, v141, s[22:23]
	v_cndmask_b32_e64 v29, v29, v30, s[22:23]
	s_waitcnt lgkmcnt(15)
	s_andn2_b64 vcc, exec, s[82:83]
	s_cbranch_vccnz .Lb4_fold_done
	v_fma_f32 v36, v160, v36, v161
	v_fma_f32 v37, v162, v37, v163
	v_fma_f32 v38, v164, v38, v165
	v_fma_f32 v39, v166, v39, v167
	s_andn2_b64 vcc, exec, s[84:85]
	s_cbranch_vccnz .Lb4_fold_done
	v_fma_f32 v36, v168, v36, v169
	v_fma_f32 v37, v170, v37, v171
	v_fma_f32 v38, v172, v38, v173
	v_fma_f32 v39, v174, v39, v175
	s_andn2_b64 vcc, exec, s[86:87]
	s_cbranch_vccnz .Lb4_fold_done
	v_fma_f32 v36, v176, v36, v177
	v_fma_f32 v37, v178, v37, v179
	v_fma_f32 v38, v180, v38, v181
	v_fma_f32 v39, v182, v39, v183
	s_andn2_b64 vcc, exec, s[88:89]
	s_cbranch_vccnz .Lb4_fold_done
	v_fma_f32 v36, v184, v36, v185
	v_fma_f32 v37, v186, v37, v187
	v_fma_f32 v38, v188, v38, v189
	v_fma_f32 v39, v190, v39, v191
	s_andn2_b64 vcc, exec, s[90:91]
	s_cbranch_vccnz .Lb4_fold_done
	v_fma_f32 v36, v192, v36, v193
	v_fma_f32 v37, v194, v37, v195
	v_fma_f32 v38, v196, v38, v197
	v_fma_f32 v39, v198, v39, v199
	s_waitcnt lgkmcnt(8)
	s_andn2_b64 vcc, exec, s[92:93]
	s_cbranch_vccnz .Lb4_fold_done
	v_fma_f32 v36, v200, v36, v201
	v_fma_f32 v37, v202, v37, v203
	v_fma_f32 v38, v204, v38, v205
	v_fma_f32 v39, v206, v39, v207
	s_andn2_b64 vcc, exec, s[94:95]
	s_cbranch_vccnz .Lb4_fold_done
	v_fma_f32 v36, v208, v36, v209
	v_fma_f32 v37, v210, v37, v211
	v_fma_f32 v38, v212, v38, v213
	v_fma_f32 v39, v214, v39, v215
